# in-projection GEMM: tile sequence permuted so the tiles with the V^T image epilogue all fall in the second round
# baseline (speedup 1.0000x reference)
; template <int K, class Epi>
; DI void gemm_phase(unsigned char* lds, int wv, const u16* A, const u16* Bt, int M, int N, Epi& epi) {
;     ...
;   for (int it = 0; it * G < Tmain; ++it) {
;     const int L = ((G & 7) == 0) ? (it * 8 + (b & 7)) * nx + (b >> 3) : it * G + b;
;     if (L < Tmain) {
;       const int grp = L / (4 * nN), rem = L - grp * (4 * nN);
;       const int gm = min(4, nM - grp * 4);
;       const int pm = grp * 4 + rem % gm, pn = rem / gm;
;       const int L2 = ((G & 7) == 0) ? ((it + 1) * 8 + (b & 7)) * nx + (b >> 3) : (it + 1) * G + b;
;       const bool has_next = L2 < Tmain;
.LBB0_90:
	s_cmpk_gt_i32 s5, 0x1f7
	s_cbranch_scc1 .LBB0_138
	s_cmpk_lt_u32 s5, 0x168
	s_cbranch_scc0 .Lremap_heavy_a
	s_mul_hi_u32 s100, s5, 0xccccccd
	s_mul_i32 s101, s100, 20
	s_sub_i32 s101, s5, s101
	s_cmp_ge_u32 s101, 8
	s_cselect_b32 s5, 4, 0
	s_add_i32 s101, s101, s5
	s_branch .Lremap_done_a
.Lremap_heavy_a:
	s_sub_i32 s101, s5, 0x168
	s_lshr_b32 s100, s101, 3
	s_and_b32 s101, s101, 7
	s_cmp_ge_u32 s101, 4
	s_cselect_b32 s5, 20, 8
	s_add_i32 s101, s101, s5
.Lremap_done_a:
	s_mul_i32 s100, s100, 28
	s_add_i32 s5, s100, s101
	s_and_b64 vcc, exec, s[70:71]
	s_cbranch_vccz .LBB0_262
	s_add_i32 s2, s22, 1
	s_mul_i32 s2, s2, s88
	s_add_i32 s6, s2, s16
	s_cbranch_execnz .LBB0_94

; template <int K, class Epi>
; DI void gemm_phase(unsigned char* lds, int wv, const u16* A, const u16* Bt, int M, int N, Epi& epi) {
;     ...
;       const int L2 = ((G & 7) == 0) ? ((it + 1) * 8 + (b & 7)) * nx + (b >> 3) : (it + 1) * G + b;
;       const bool has_next = L2 < Tmain;
;       int pm2 = 0, pn2 = 0;
;       if (has_next) { const int grp2 = L2 / (4 * nN), rem2 = L2 - grp2 * (4 * nN); const int gm2 = min(4, nM - grp2 * 4); pm2 = grp2 * 4 + rem2 % gm2; pn2 = rem2 / gm2; }
.LBB0_94:
	s_cmpk_lt_i32 s6, 0x1f8
	s_mov_b32 s2, 0
	s_cselect_b64 s[56:57], -1, 0
	s_cmpk_gt_i32 s6, 0x1f7
	s_mov_b32 s4, 0
	s_cbranch_scc1 .LBB0_96
	s_cmpk_lt_u32 s6, 0x168
	s_cbranch_scc0 .Lremap_heavy_b
	s_mul_hi_u32 s100, s6, 0xccccccd
	s_mul_i32 s101, s100, 20
	s_sub_i32 s101, s6, s101
	s_cmp_ge_u32 s101, 8
	s_cselect_b32 s6, 4, 0
	s_add_i32 s101, s101, s6
	s_branch .Lremap_done_b
.Lremap_heavy_b:
	s_sub_i32 s101, s6, 0x168
	s_lshr_b32 s100, s101, 3
	s_and_b32 s101, s101, 7
	s_cmp_ge_u32 s101, 4
	s_cselect_b32 s6, 20, 8
	s_add_i32 s101, s101, s6
.Lremap_done_b:
	s_mul_i32 s100, s100, 28
	s_add_i32 s6, s100, s101
	s_mul_hi_i32 s2, s6, 0x92492493
	s_add_i32 s2, s2, s6
	s_lshr_b32 s3, s2, 31
	s_ashr_i32 s2, s2, 4
	s_add_i32 s2, s2, s3
	s_mul_i32 s3, s2, 0xffffffe4
	s_add_i32 s3, s3, s6
	s_ashr_i32 s4, s3, 31
	s_lshr_b32 s4, s4, 30
	s_add_i32 s6, s3, s4
	s_and_b32 s4, s6, 0xfffffc
	s_sub_i32 s3, s3, s4
	s_lshl_b32 s2, s2, 10
	s_lshl_b32 s3, s3, 8
	s_add_i32 s4, s3, s2
	s_lshl_b32 s2, s6, 6
	s_and_b32 s2, s2, 0xffffff00
